# weight-transpose loops with a norm gain (w_in, w_gate_up; P0 and layer-0 idle slots): 32 W + 32 gain loads issued before the first counted wait instead of one serialised load per step
# speedup vs baseline: 1.0320x; 1.0261x over previous
; template <bool GU>
; __device__ __forceinline__ void transpose_item(const float* W, int K, int N, bf16* WT, const float* gs, LAS float* scr, int item, int lane) {
;     const int nblk = N / 32, kb = item / nblk, nb = item % nblk, k0 = 64 * kb, n0 = 32 * nb;
; #pragma unroll 16
;     for (int i = 0; i < 32; ++i) { const int kk = 2 * i + (lane >> 5); float w = W[(size_t)(k0 + kk) * N + n0 + (lane & 31)]; if (gs) w *= gs[k0 + kk]; scr[kk * 33 + (lane & 31)] = w; }
; __device__ __forceinline__ void conv_weights(LAS unsigned char* lds, unsigned char* ws, const PIn& I, const int l, const int wave, const int lane, const int gw, const int NGW, const int r_lo, const int r_hi) {
;     ...
;         if (r < I_IN) { transpose_item<false>(I.w_in + (size_t)l * DM * NIN, DM, NIN, (bf16*)(wb + W_IN), I.g_mix + l * DM, scr, r, lane); continue; } r -= I_IN;
.LBB0_19:
	s_mul_hi_i32 s4, s3, 0x38e38e39
	s_lshr_b32 s5, s4, 31
	s_ashr_i32 s4, s4, 4
	s_add_i32 s4, s4, s5
	s_mul_i32 s5, s4, 0x48
	s_sub_i32 s5, s3, s5
	s_lshl_b32 s12, s5, 5
	s_lshl_b32 s14, s4, 6
	s_ashr_i32 s13, s12, 31
	s_lshl_b64 s[4:5], s[12:13], 2
	v_add_u32_e32 v50, s14, v14
	s_ashr_i32 s15, s14, 31
	v_ashrrev_i32_e32 v51, 31, v50
	v_mov_b64_e32 v[52:53], s[4:5]
	v_lshl_add_u64 v[44:45], v[10:11], 0, s[4:5]
	v_lshl_add_u64 v[46:47], v[14:15], 0, s[14:15]
	v_lshl_add_u64 v[48:49], v[50:51], 2, s[76:77]
	v_mad_i64_i32 v[50:51], s[4:5], v50, s2, v[52:53]
	v_add_u32_e32 v93, s14, v25
	v_lshl_add_u64 v[46:47], v[46:47], 2, s[76:77]
	v_lshl_add_u64 v[50:51], v[10:11], 0, v[50:51]
	s_mov_b64 s[16:17], 0
	v_mov_b32_e32 v94, v61
	s_andn2_b64 vcc, exec, s[8:9]
	s_cbranch_vccnz .LBB0_21
	s_mov_b64 s[58:59], 0x4800
	v_mov_b32_e32 v234, v50
	v_mov_b32_e32 v235, v51
	v_mov_b32_e32 v236, v48
	v_mov_b32_e32 v237, v49
	global_load_dword v166, v[234:235], off
	v_lshl_add_u64 v[234:235], v[234:235], 0, s[58:59]
	global_load_dword v167, v[234:235], off
	v_lshl_add_u64 v[234:235], v[234:235], 0, s[58:59]
	global_load_dword v168, v[234:235], off
	v_lshl_add_u64 v[234:235], v[234:235], 0, s[58:59]
	global_load_dword v169, v[234:235], off
	v_lshl_add_u64 v[234:235], v[234:235], 0, s[58:59]
	global_load_dword v170, v[234:235], off
	v_lshl_add_u64 v[234:235], v[234:235], 0, s[58:59]
	global_load_dword v171, v[234:235], off
	v_lshl_add_u64 v[234:235], v[234:235], 0, s[58:59]
	global_load_dword v172, v[234:235], off
	v_lshl_add_u64 v[234:235], v[234:235], 0, s[58:59]
	global_load_dword v173, v[234:235], off
	v_lshl_add_u64 v[234:235], v[234:235], 0, s[58:59]
	global_load_dword v174, v[234:235], off
	v_lshl_add_u64 v[234:235], v[234:235], 0, s[58:59]
	global_load_dword v175, v[234:235], off
	v_lshl_add_u64 v[234:235], v[234:235], 0, s[58:59]
	global_load_dword v176, v[234:235], off
	v_lshl_add_u64 v[234:235], v[234:235], 0, s[58:59]
	global_load_dword v177, v[234:235], off
	v_lshl_add_u64 v[234:235], v[234:235], 0, s[58:59]
	global_load_dword v178, v[234:235], off
	v_lshl_add_u64 v[234:235], v[234:235], 0, s[58:59]
	global_load_dword v179, v[234:235], off
	v_lshl_add_u64 v[234:235], v[234:235], 0, s[58:59]
	global_load_dword v180, v[234:235], off
	v_lshl_add_u64 v[234:235], v[234:235], 0, s[58:59]
	global_load_dword v181, v[234:235], off
	v_lshl_add_u64 v[234:235], v[234:235], 0, s[58:59]
	global_load_dword v182, v[234:235], off
	v_lshl_add_u64 v[234:235], v[234:235], 0, s[58:59]
	global_load_dword v183, v[234:235], off
	v_lshl_add_u64 v[234:235], v[234:235], 0, s[58:59]
	global_load_dword v184, v[234:235], off
	v_lshl_add_u64 v[234:235], v[234:235], 0, s[58:59]
	global_load_dword v185, v[234:235], off
	v_lshl_add_u64 v[234:235], v[234:235], 0, s[58:59]
	global_load_dword v186, v[234:235], off
	v_lshl_add_u64 v[234:235], v[234:235], 0, s[58:59]
	global_load_dword v187, v[234:235], off
	v_lshl_add_u64 v[234:235], v[234:235], 0, s[58:59]
	global_load_dword v188, v[234:235], off
	v_lshl_add_u64 v[234:235], v[234:235], 0, s[58:59]
	global_load_dword v189, v[234:235], off
	v_lshl_add_u64 v[234:235], v[234:235], 0, s[58:59]
	global_load_dword v190, v[234:235], off
	v_lshl_add_u64 v[234:235], v[234:235], 0, s[58:59]
	global_load_dword v191, v[234:235], off
	v_lshl_add_u64 v[234:235], v[234:235], 0, s[58:59]
	global_load_dword v192, v[234:235], off
	v_lshl_add_u64 v[234:235], v[234:235], 0, s[58:59]
	global_load_dword v193, v[234:235], off
	v_lshl_add_u64 v[234:235], v[234:235], 0, s[58:59]
	global_load_dword v194, v[234:235], off
	v_lshl_add_u64 v[234:235], v[234:235], 0, s[58:59]
	global_load_dword v195, v[234:235], off
	v_lshl_add_u64 v[234:235], v[234:235], 0, s[58:59]
	global_load_dword v199, v[234:235], off
	v_lshl_add_u64 v[234:235], v[234:235], 0, s[58:59]
	global_load_dword v200, v[234:235], off
	global_load_dword v201, v[236:237], off
	global_load_dword v202, v[236:237], off offset:8
	global_load_dword v203, v[236:237], off offset:16
	global_load_dword v204, v[236:237], off offset:24
	global_load_dword v205, v[236:237], off offset:32
	global_load_dword v206, v[236:237], off offset:40
	global_load_dword v207, v[236:237], off offset:48
	global_load_dword v208, v[236:237], off offset:56
	global_load_dword v209, v[236:237], off offset:64
	global_load_dword v210, v[236:237], off offset:72
	global_load_dword v211, v[236:237], off offset:80
	global_load_dword v212, v[236:237], off offset:88
	global_load_dword v213, v[236:237], off offset:96
	global_load_dword v214, v[236:237], off offset:104
	global_load_dword v215, v[236:237], off offset:112
	global_load_dword v216, v[236:237], off offset:120
	global_load_dword v217, v[236:237], off offset:128
	global_load_dword v218, v[236:237], off offset:136
	global_load_dword v219, v[236:237], off offset:144
	global_load_dword v220, v[236:237], off offset:152
	global_load_dword v221, v[236:237], off offset:160
	global_load_dword v222, v[236:237], off offset:168
	global_load_dword v223, v[236:237], off offset:176
	global_load_dword v224, v[236:237], off offset:184
	global_load_dword v225, v[236:237], off offset:192
	global_load_dword v226, v[236:237], off offset:200
	global_load_dword v227, v[236:237], off offset:208
	global_load_dword v228, v[236:237], off offset:216
	global_load_dword v229, v[236:237], off offset:224
	global_load_dword v230, v[236:237], off offset:232
	global_load_dword v231, v[236:237], off offset:240
	global_load_dword v232, v[236:237], off offset:248
	s_waitcnt vmcnt(31)
; template <bool GU>
; __device__ __forceinline__ void transpose_item(const float* W, int K, int N, bf16* WT, const float* gs, LAS float* scr, int item, int lane) {
;     ...
;     for (int i = 0; i < 32; ++i) { const int kk = 2 * i + (lane >> 5); float w = W[(size_t)(k0 + kk) * N + n0 + (lane & 31)]; if (gs) w *= gs[k0 + kk]; scr[kk * 33 + (lane & 31)] = w; }
	v_mul_f32_e32 v166, v166, v201
	ds_write_b32 v94, v166
	s_waitcnt vmcnt(30)
	v_mul_f32_e32 v167, v167, v202
	ds_write_b32 v94, v167 offset:264
	s_waitcnt vmcnt(29)
	v_mul_f32_e32 v168, v168, v203
	ds_write_b32 v94, v168 offset:528
	s_waitcnt vmcnt(28)
	v_mul_f32_e32 v169, v169, v204
	ds_write_b32 v94, v169 offset:792
	s_waitcnt vmcnt(27)
	v_mul_f32_e32 v170, v170, v205
	ds_write_b32 v94, v170 offset:1056
	s_waitcnt vmcnt(26)
	v_mul_f32_e32 v171, v171, v206
	ds_write_b32 v94, v171 offset:1320
	s_waitcnt vmcnt(25)
	v_mul_f32_e32 v172, v172, v207
	ds_write_b32 v94, v172 offset:1584
	s_waitcnt vmcnt(24)
	v_mul_f32_e32 v173, v173, v208
	ds_write_b32 v94, v173 offset:1848
	s_waitcnt vmcnt(23)
	v_mul_f32_e32 v174, v174, v209
	ds_write_b32 v94, v174 offset:2112
	s_waitcnt vmcnt(22)
	v_mul_f32_e32 v175, v175, v210
	ds_write_b32 v94, v175 offset:2376
	s_waitcnt vmcnt(21)
	v_mul_f32_e32 v176, v176, v211
	ds_write_b32 v94, v176 offset:2640
	s_waitcnt vmcnt(20)
	v_mul_f32_e32 v177, v177, v212
	ds_write_b32 v94, v177 offset:2904
	s_waitcnt vmcnt(19)
	v_mul_f32_e32 v178, v178, v213
	ds_write_b32 v94, v178 offset:3168
	s_waitcnt vmcnt(18)
	v_mul_f32_e32 v179, v179, v214
	ds_write_b32 v94, v179 offset:3432
	s_waitcnt vmcnt(17)
	v_mul_f32_e32 v180, v180, v215
	ds_write_b32 v94, v180 offset:3696
	s_waitcnt vmcnt(16)
	v_mul_f32_e32 v181, v181, v216
	ds_write_b32 v94, v181 offset:3960
	s_waitcnt vmcnt(15)
	v_mul_f32_e32 v182, v182, v217
	ds_write_b32 v94, v182 offset:4224
	s_waitcnt vmcnt(14)
	v_mul_f32_e32 v183, v183, v218
	ds_write_b32 v94, v183 offset:4488
	s_waitcnt vmcnt(13)
	v_mul_f32_e32 v184, v184, v219
	ds_write_b32 v94, v184 offset:4752
	s_waitcnt vmcnt(12)
	v_mul_f32_e32 v185, v185, v220
	ds_write_b32 v94, v185 offset:5016
	s_waitcnt vmcnt(11)
	v_mul_f32_e32 v186, v186, v221
	ds_write_b32 v94, v186 offset:5280
	s_waitcnt vmcnt(10)
	v_mul_f32_e32 v187, v187, v222
	ds_write_b32 v94, v187 offset:5544
	s_waitcnt vmcnt(9)
	v_mul_f32_e32 v188, v188, v223
	ds_write_b32 v94, v188 offset:5808
	s_waitcnt vmcnt(8)
	v_mul_f32_e32 v189, v189, v224
	ds_write_b32 v94, v189 offset:6072
	s_waitcnt vmcnt(7)
	v_mul_f32_e32 v190, v190, v225
	ds_write_b32 v94, v190 offset:6336
	s_waitcnt vmcnt(6)
	v_mul_f32_e32 v191, v191, v226
	ds_write_b32 v94, v191 offset:6600
	s_waitcnt vmcnt(5)
	v_mul_f32_e32 v192, v192, v227
	ds_write_b32 v94, v192 offset:6864
	s_waitcnt vmcnt(4)
	v_mul_f32_e32 v193, v193, v228
	ds_write_b32 v94, v193 offset:7128
	s_waitcnt vmcnt(3)
	v_mul_f32_e32 v194, v194, v229
	ds_write_b32 v94, v194 offset:7392
	s_waitcnt vmcnt(2)
	v_mul_f32_e32 v195, v195, v230
	ds_write_b32 v94, v195 offset:7656
	s_waitcnt vmcnt(1)
	v_mul_f32_e32 v199, v199, v231
	ds_write_b32 v94, v199 offset:7920
	s_waitcnt vmcnt(0)
	v_mul_f32_e32 v200, v200, v232
	ds_write_b32 v94, v200 offset:8184
	s_branch .LBB0_14

; template <bool GU>
; __device__ __forceinline__ void transpose_item(const float* W, int K, int N, bf16* WT, const float* gs, LAS float* scr, int item, int lane) {
;     const int nblk = N / 32, kb = item / nblk, nb = item % nblk, k0 = 64 * kb, n0 = 32 * nb;
; #pragma unroll 16
;     for (int i = 0; i < 32; ++i) { const int kk = 2 * i + (lane >> 5); float w = W[(size_t)(k0 + kk) * N + n0 + (lane & 31)]; if (gs) w *= gs[k0 + kk]; scr[kk * 33 + (lane & 31)] = w; }
; __device__ __forceinline__ void conv_weights(LAS unsigned char* lds, unsigned char* ws, const PIn& I, const int l, const int wave, const int lane, const int gw, const int NGW, const int r_lo, const int r_hi) {
;     ...
;         if (r < I_GU) { transpose_item<true>(I.w_gu + (size_t)l * DM * 2 * FF, DM, 2 * FF, (bf16*)(wb + W_GU), I.g_ffn + l * DM, scr, r, lane); continue; } r -= I_GU;
.LBB0_497:
	s_andn2_b64 vcc, exec, s[6:7]
	s_cbranch_vccnz .LBB0_533
	s_add_i32 s6, s1, 0xf980
	s_and_b32 s30, s6, 0xffff
	s_mul_i32 s7, s30, 0xba2f
	s_lshr_b32 s7, s7, 23
	s_mul_i32 s9, s7, 0xb0
	s_sub_i32 s29, s6, s9
	s_lshl_b32 s6, s29, 7
	s_lshl_b32 s9, s7, 6
	s_and_b32 s10, s6, 0x3ff80
	v_add_u32_e32 v60, s9, v37
	v_mov_b64_e32 v[94:95], s[10:11]
	v_mad_i64_i32 v[60:61], s[6:7], v60, s3, v[94:95]
	s_mul_hi_u32 s6, s30, 0x1745d18
	v_add_u32_e32 v64, s9, v36
	v_add_u32_e32 v66, s9, v35
	v_add_u32_e32 v68, s9, v34
	v_add_u32_e32 v70, s9, v33
	v_add_u32_e32 v72, s9, v32
	v_add_u32_e32 v74, s9, v31
	v_add_u32_e32 v76, s9, v30
	v_add_u32_e32 v78, s9, v29
	v_add_u32_e32 v80, s9, v28
	v_add_u32_e32 v82, s9, v27
	v_add_u32_e32 v84, s9, v26
	v_add_u32_e32 v86, s9, v25
	v_add_u32_e32 v88, s9, v24
	v_add_u32_e32 v90, s9, v1
	v_add_u32_e32 v96, s9, v54
	v_readlane_b32 s48, v249, 21
	s_lshl_b32 s10, s6, 8
	v_mad_i64_i32 v[64:65], s[6:7], v64, s3, v[94:95]
	v_mad_i64_i32 v[66:67], s[6:7], v66, s3, v[94:95]
	v_mad_i64_i32 v[68:69], s[6:7], v68, s3, v[94:95]
	v_mad_i64_i32 v[70:71], s[6:7], v70, s3, v[94:95]
	v_mad_i64_i32 v[72:73], s[6:7], v72, s3, v[94:95]
	v_mad_i64_i32 v[74:75], s[6:7], v74, s3, v[94:95]
	v_mad_i64_i32 v[76:77], s[6:7], v76, s3, v[94:95]
	v_mad_i64_i32 v[78:79], s[6:7], v78, s3, v[94:95]
	v_mad_i64_i32 v[80:81], s[6:7], v80, s3, v[94:95]
	v_mad_i64_i32 v[82:83], s[6:7], v82, s3, v[94:95]
	v_mad_i64_i32 v[84:85], s[6:7], v84, s3, v[94:95]
	v_mad_i64_i32 v[86:87], s[6:7], v86, s3, v[94:95]
	v_mad_i64_i32 v[88:89], s[6:7], v88, s3, v[94:95]
	v_mad_i64_i32 v[90:91], s[6:7], v90, s3, v[94:95]
	v_ashrrev_i32_e32 v97, 31, v96
	v_mad_i64_i32 v[94:95], s[6:7], v96, s3, v[94:95]
	v_readlane_b32 s62, v249, 35
	v_readlane_b32 s63, v249, 36
	s_lshl_b32 s36, s29, 5
	v_lshl_add_u64 v[60:61], v[56:57], 0, v[60:61]
	v_lshl_add_u64 v[62:63], v[58:59], 0, s[10:11]
	v_lshl_add_u64 v[64:65], v[56:57], 0, v[64:65]
	v_lshl_add_u64 v[66:67], v[56:57], 0, v[66:67]
	v_lshl_add_u64 v[68:69], v[56:57], 0, v[68:69]
	v_lshl_add_u64 v[70:71], v[56:57], 0, v[70:71]
	v_lshl_add_u64 v[72:73], v[56:57], 0, v[72:73]
	v_lshl_add_u64 v[74:75], v[56:57], 0, v[74:75]
	v_lshl_add_u64 v[76:77], v[56:57], 0, v[76:77]
	v_lshl_add_u64 v[78:79], v[56:57], 0, v[78:79]
	v_lshl_add_u64 v[80:81], v[56:57], 0, v[80:81]
	v_lshl_add_u64 v[82:83], v[56:57], 0, v[82:83]
	v_lshl_add_u64 v[84:85], v[56:57], 0, v[84:85]
	v_lshl_add_u64 v[86:87], v[56:57], 0, v[86:87]
	v_lshl_add_u64 v[88:89], v[56:57], 0, v[88:89]
	v_lshl_add_u64 v[90:91], v[56:57], 0, v[90:91]
	v_lshlrev_b64 v[92:93], 2, v[96:97]
	v_lshl_add_u64 v[94:95], v[56:57], 0, v[94:95]
	s_mov_b64 s[30:31], 0
	s_mov_b64 s[42:43], s[62:63]
	v_mov_b32_e32 v137, v136
	v_readlane_b32 s49, v249, 22
	v_readlane_b32 s50, v249, 23
	v_readlane_b32 s51, v249, 24
	v_readlane_b32 s52, v249, 25
	v_readlane_b32 s53, v249, 26
	v_readlane_b32 s54, v249, 27
	v_readlane_b32 s55, v249, 28
	v_readlane_b32 s56, v249, 29
	v_readlane_b32 s57, v249, 30
	v_readlane_b32 s58, v249, 31
	v_readlane_b32 s59, v249, 32
	v_readlane_b32 s60, v249, 33
	v_readlane_b32 s61, v249, 34
	s_andn2_b64 vcc, exec, s[12:13]
	s_cbranch_vccnz .LBB0_500
	s_mov_b64 s[58:59], 0xb000
	v_mov_b32_e32 v234, v94
	v_mov_b32_e32 v235, v95
	v_lshl_add_u64 v[236:237], s[42:43], 0, v[92:93]
	global_load_dword v166, v[234:235], off
	v_lshl_add_u64 v[234:235], v[234:235], 0, s[58:59]
	global_load_dword v167, v[234:235], off
	v_lshl_add_u64 v[234:235], v[234:235], 0, s[58:59]
	global_load_dword v168, v[234:235], off
	v_lshl_add_u64 v[234:235], v[234:235], 0, s[58:59]
	global_load_dword v169, v[234:235], off
	v_lshl_add_u64 v[234:235], v[234:235], 0, s[58:59]
	global_load_dword v170, v[234:235], off
	v_lshl_add_u64 v[234:235], v[234:235], 0, s[58:59]
	global_load_dword v171, v[234:235], off
	v_lshl_add_u64 v[234:235], v[234:235], 0, s[58:59]
	global_load_dword v172, v[234:235], off
	v_lshl_add_u64 v[234:235], v[234:235], 0, s[58:59]
	global_load_dword v173, v[234:235], off
	v_lshl_add_u64 v[234:235], v[234:235], 0, s[58:59]
	global_load_dword v174, v[234:235], off
	v_lshl_add_u64 v[234:235], v[234:235], 0, s[58:59]
	global_load_dword v175, v[234:235], off
	v_lshl_add_u64 v[234:235], v[234:235], 0, s[58:59]
	global_load_dword v176, v[234:235], off
	v_lshl_add_u64 v[234:235], v[234:235], 0, s[58:59]
	global_load_dword v177, v[234:235], off
	v_lshl_add_u64 v[234:235], v[234:235], 0, s[58:59]
	global_load_dword v178, v[234:235], off
	v_lshl_add_u64 v[234:235], v[234:235], 0, s[58:59]
	global_load_dword v179, v[234:235], off
	v_lshl_add_u64 v[234:235], v[234:235], 0, s[58:59]
	global_load_dword v180, v[234:235], off
	v_lshl_add_u64 v[234:235], v[234:235], 0, s[58:59]
	global_load_dword v181, v[234:235], off
	v_lshl_add_u64 v[234:235], v[234:235], 0, s[58:59]
	global_load_dword v182, v[234:235], off
	v_lshl_add_u64 v[234:235], v[234:235], 0, s[58:59]
	global_load_dword v183, v[234:235], off
	v_lshl_add_u64 v[234:235], v[234:235], 0, s[58:59]
	global_load_dword v184, v[234:235], off
	v_lshl_add_u64 v[234:235], v[234:235], 0, s[58:59]
	global_load_dword v185, v[234:235], off
	v_lshl_add_u64 v[234:235], v[234:235], 0, s[58:59]
	global_load_dword v186, v[234:235], off
	v_lshl_add_u64 v[234:235], v[234:235], 0, s[58:59]
	global_load_dword v187, v[234:235], off
	v_lshl_add_u64 v[234:235], v[234:235], 0, s[58:59]
	global_load_dword v188, v[234:235], off
; template <bool GU>
; __device__ __forceinline__ void transpose_item(const float* W, int K, int N, bf16* WT, const float* gs, LAS float* scr, int item, int lane) {
;     ...
;     for (int i = 0; i < 32; ++i) { const int kk = 2 * i + (lane >> 5); float w = W[(size_t)(k0 + kk) * N + n0 + (lane & 31)]; if (gs) w *= gs[k0 + kk]; scr[kk * 33 + (lane & 31)] = w; }
	v_lshl_add_u64 v[234:235], v[234:235], 0, s[58:59]
	global_load_dword v189, v[234:235], off
	v_lshl_add_u64 v[234:235], v[234:235], 0, s[58:59]
	global_load_dword v190, v[234:235], off
	v_lshl_add_u64 v[234:235], v[234:235], 0, s[58:59]
	global_load_dword v191, v[234:235], off
	v_lshl_add_u64 v[234:235], v[234:235], 0, s[58:59]
	global_load_dword v192, v[234:235], off
	v_lshl_add_u64 v[234:235], v[234:235], 0, s[58:59]
	global_load_dword v193, v[234:235], off
	v_lshl_add_u64 v[234:235], v[234:235], 0, s[58:59]
	global_load_dword v194, v[234:235], off
	v_lshl_add_u64 v[234:235], v[234:235], 0, s[58:59]
	global_load_dword v195, v[234:235], off
	v_lshl_add_u64 v[234:235], v[234:235], 0, s[58:59]
	global_load_dword v199, v[234:235], off
	v_lshl_add_u64 v[234:235], v[234:235], 0, s[58:59]
	global_load_dword v200, v[234:235], off
	global_load_dword v201, v[236:237], off
	global_load_dword v202, v[236:237], off offset:8
	global_load_dword v203, v[236:237], off offset:16
	global_load_dword v204, v[236:237], off offset:24
	global_load_dword v205, v[236:237], off offset:32
	global_load_dword v206, v[236:237], off offset:40
	global_load_dword v207, v[236:237], off offset:48
	global_load_dword v208, v[236:237], off offset:56
	global_load_dword v209, v[236:237], off offset:64
	global_load_dword v210, v[236:237], off offset:72
	global_load_dword v211, v[236:237], off offset:80
	global_load_dword v212, v[236:237], off offset:88
	global_load_dword v213, v[236:237], off offset:96
	global_load_dword v214, v[236:237], off offset:104
	global_load_dword v215, v[236:237], off offset:112
	global_load_dword v216, v[236:237], off offset:120
	global_load_dword v217, v[236:237], off offset:128
	global_load_dword v218, v[236:237], off offset:136
	global_load_dword v219, v[236:237], off offset:144
	global_load_dword v220, v[236:237], off offset:152
	global_load_dword v221, v[236:237], off offset:160
	global_load_dword v222, v[236:237], off offset:168
	global_load_dword v223, v[236:237], off offset:176
	global_load_dword v224, v[236:237], off offset:184
	global_load_dword v225, v[236:237], off offset:192
	global_load_dword v226, v[236:237], off offset:200
	global_load_dword v227, v[236:237], off offset:208
	global_load_dword v228, v[236:237], off offset:216
	global_load_dword v229, v[236:237], off offset:224
	global_load_dword v230, v[236:237], off offset:232
	global_load_dword v231, v[236:237], off offset:240
	global_load_dword v232, v[236:237], off offset:248
	s_waitcnt vmcnt(31)
	v_mul_f32_e32 v166, v166, v201
	ds_write_b32 v137, v166
	s_waitcnt vmcnt(30)
	v_mul_f32_e32 v167, v167, v202
	ds_write_b32 v137, v167 offset:264
	s_waitcnt vmcnt(29)
	v_mul_f32_e32 v168, v168, v203
	ds_write_b32 v137, v168 offset:528
	s_waitcnt vmcnt(28)
	v_mul_f32_e32 v169, v169, v204
	ds_write_b32 v137, v169 offset:792
	s_waitcnt vmcnt(27)
	v_mul_f32_e32 v170, v170, v205
	ds_write_b32 v137, v170 offset:1056
	s_waitcnt vmcnt(26)
	v_mul_f32_e32 v171, v171, v206
	ds_write_b32 v137, v171 offset:1320
	s_waitcnt vmcnt(25)
	v_mul_f32_e32 v172, v172, v207
	ds_write_b32 v137, v172 offset:1584
	s_waitcnt vmcnt(24)
	v_mul_f32_e32 v173, v173, v208
	ds_write_b32 v137, v173 offset:1848
	s_waitcnt vmcnt(23)
	v_mul_f32_e32 v174, v174, v209
	ds_write_b32 v137, v174 offset:2112
	s_waitcnt vmcnt(22)
	v_mul_f32_e32 v175, v175, v210
	ds_write_b32 v137, v175 offset:2376
	s_waitcnt vmcnt(21)
	v_mul_f32_e32 v176, v176, v211
	ds_write_b32 v137, v176 offset:2640
	s_waitcnt vmcnt(20)
	v_mul_f32_e32 v177, v177, v212
	ds_write_b32 v137, v177 offset:2904
	s_waitcnt vmcnt(19)
	v_mul_f32_e32 v178, v178, v213
	ds_write_b32 v137, v178 offset:3168
	s_waitcnt vmcnt(18)
	v_mul_f32_e32 v179, v179, v214
	ds_write_b32 v137, v179 offset:3432
	s_waitcnt vmcnt(17)
	v_mul_f32_e32 v180, v180, v215
	ds_write_b32 v137, v180 offset:3696
	s_waitcnt vmcnt(16)
	v_mul_f32_e32 v181, v181, v216
	ds_write_b32 v137, v181 offset:3960
	s_waitcnt vmcnt(15)
	v_mul_f32_e32 v182, v182, v217
	ds_write_b32 v137, v182 offset:4224
	s_waitcnt vmcnt(14)
	v_mul_f32_e32 v183, v183, v218
	ds_write_b32 v137, v183 offset:4488
	s_waitcnt vmcnt(13)
	v_mul_f32_e32 v184, v184, v219
	ds_write_b32 v137, v184 offset:4752
	s_waitcnt vmcnt(12)
	v_mul_f32_e32 v185, v185, v220
	ds_write_b32 v137, v185 offset:5016
	s_waitcnt vmcnt(11)
	v_mul_f32_e32 v186, v186, v221
	ds_write_b32 v137, v186 offset:5280
	s_waitcnt vmcnt(10)
	v_mul_f32_e32 v187, v187, v222
	ds_write_b32 v137, v187 offset:5544
	s_waitcnt vmcnt(9)
	v_mul_f32_e32 v188, v188, v223
	ds_write_b32 v137, v188 offset:5808
	s_waitcnt vmcnt(8)
	v_mul_f32_e32 v189, v189, v224
	ds_write_b32 v137, v189 offset:6072
	s_waitcnt vmcnt(7)
	v_mul_f32_e32 v190, v190, v225
	ds_write_b32 v137, v190 offset:6336
	s_waitcnt vmcnt(6)
	v_mul_f32_e32 v191, v191, v226
	ds_write_b32 v137, v191 offset:6600
	s_waitcnt vmcnt(5)
	v_mul_f32_e32 v192, v192, v227
	ds_write_b32 v137, v192 offset:6864
	s_waitcnt vmcnt(4)
	v_mul_f32_e32 v193, v193, v228
	ds_write_b32 v137, v193 offset:7128
	s_waitcnt vmcnt(3)
	v_mul_f32_e32 v194, v194, v229
	ds_write_b32 v137, v194 offset:7392
	s_waitcnt vmcnt(2)
	v_mul_f32_e32 v195, v195, v230
	ds_write_b32 v137, v195 offset:7656
	s_waitcnt vmcnt(1)
	v_mul_f32_e32 v199, v199, v231
	ds_write_b32 v137, v199 offset:7920
	s_waitcnt vmcnt(0)
	v_mul_f32_e32 v200, v200, v232
	ds_write_b32 v137, v200 offset:8184
	s_branch .LBB0_532

; template <bool GU>
; __device__ __forceinline__ void transpose_item(const float* W, int K, int N, bf16* WT, const float* gs, LAS float* scr, int item, int lane) {
;     const int nblk = N / 32, kb = item / nblk, nb = item % nblk, k0 = 64 * kb, n0 = 32 * nb;
; #pragma unroll 16
;     for (int i = 0; i < 32; ++i) { const int kk = 2 * i + (lane >> 5); float w = W[(size_t)(k0 + kk) * N + n0 + (lane & 31)]; if (gs) w *= gs[k0 + kk]; scr[kk * 33 + (lane & 31)] = w; }
; __device__ __forceinline__ void conv_weights(LAS unsigned char* lds, unsigned char* ws, const PIn& I, const int l, const int wave, const int lane, const int gw, const int NGW, const int r_lo, const int r_hi) {
;     ...
;         if (r < I_GU) { transpose_item<true>(I.w_gu + (size_t)l * DM * 2 * FF, DM, 2 * FF, (bf16*)(wb + W_GU), I.g_ffn + l * DM, scr, r, lane); continue; } r -= I_GU;
.LBB0_718:
	s_andn2_b64 vcc, exec, s[6:7]
	s_cbranch_vccnz .LBB0_754
	s_add_i32 s6, s0, 0xf980
	s_and_b32 s10, s6, 0xffff
	s_mul_i32 s7, s10, 0xba2f
	s_lshr_b32 s7, s7, 23
	s_mul_i32 s40, s7, 0xb0
	s_sub_i32 s41, s6, s40
	s_lshl_b32 s6, s41, 7
	s_lshl_b32 s40, s7, 6
	s_lshl_b32 s50, s41, 5
	s_and_b32 s48, s6, 0x3ff80
	s_add_u32 s6, s2, s48
	v_add_u32_e32 v64, s40, v39
	s_addc_u32 s7, s3, 0
	v_add_u32_e32 v68, s40, v38
	v_add_u32_e32 v72, s40, v37
	v_add_u32_e32 v76, s40, v36
	v_add_u32_e32 v80, s40, v35
	v_add_u32_e32 v84, s40, v34
	v_add_u32_e32 v88, s40, v33
	v_add_u32_e32 v92, s40, v32
	v_add_u32_e32 v96, s40, v31
	v_add_u32_e32 v100, s40, v30
	v_add_u32_e32 v104, s40, v29
	v_add_u32_e32 v108, s40, v28
	v_add_u32_e32 v112, s40, v27
	v_add_u32_e32 v116, s40, v26
	v_ashrrev_i32_e32 v65, 31, v64
	v_mov_b64_e32 v[120:121], s[6:7]
	v_ashrrev_i32_e32 v69, 31, v68
	v_ashrrev_i32_e32 v73, 31, v72
	v_ashrrev_i32_e32 v77, 31, v76
	v_ashrrev_i32_e32 v81, 31, v80
	v_ashrrev_i32_e32 v85, 31, v84
	v_ashrrev_i32_e32 v89, 31, v88
	v_ashrrev_i32_e32 v93, 31, v92
	v_ashrrev_i32_e32 v97, 31, v96
	v_ashrrev_i32_e32 v101, 31, v100
	v_ashrrev_i32_e32 v105, 31, v104
	v_ashrrev_i32_e32 v109, 31, v108
	v_ashrrev_i32_e32 v113, 31, v112
	v_ashrrev_i32_e32 v117, 31, v116
	v_add_u32_e32 v122, s40, v1
	v_lshl_add_u64 v[62:63], v[64:65], 2, s[30:31]
	v_mad_i64_i32 v[64:65], s[6:7], v64, s18, v[120:121]
	v_lshl_add_u64 v[66:67], v[68:69], 2, s[30:31]
	v_mad_i64_i32 v[68:69], s[6:7], v68, s18, v[120:121]
	v_lshl_add_u64 v[70:71], v[72:73], 2, s[30:31]
	v_mad_i64_i32 v[72:73], s[6:7], v72, s18, v[120:121]
	v_lshl_add_u64 v[74:75], v[76:77], 2, s[30:31]
	v_mad_i64_i32 v[76:77], s[6:7], v76, s18, v[120:121]
	v_lshl_add_u64 v[78:79], v[80:81], 2, s[30:31]
	v_mad_i64_i32 v[80:81], s[6:7], v80, s18, v[120:121]
	v_lshl_add_u64 v[82:83], v[84:85], 2, s[30:31]
	v_mad_i64_i32 v[84:85], s[6:7], v84, s18, v[120:121]
	v_lshl_add_u64 v[86:87], v[88:89], 2, s[30:31]
	v_mad_i64_i32 v[88:89], s[6:7], v88, s18, v[120:121]
	v_lshl_add_u64 v[90:91], v[92:93], 2, s[30:31]
	v_mad_i64_i32 v[92:93], s[6:7], v92, s18, v[120:121]
	v_lshl_add_u64 v[94:95], v[96:97], 2, s[30:31]
	v_mad_i64_i32 v[96:97], s[6:7], v96, s18, v[120:121]
	v_lshl_add_u64 v[98:99], v[100:101], 2, s[30:31]
	v_mad_i64_i32 v[100:101], s[6:7], v100, s18, v[120:121]
	v_lshl_add_u64 v[102:103], v[104:105], 2, s[30:31]
	v_mad_i64_i32 v[104:105], s[6:7], v104, s18, v[120:121]
	v_lshl_add_u64 v[106:107], v[108:109], 2, s[30:31]
	v_mad_i64_i32 v[108:109], s[6:7], v108, s18, v[120:121]
	v_lshl_add_u64 v[110:111], v[112:113], 2, s[30:31]
	v_mad_i64_i32 v[112:113], s[6:7], v112, s18, v[120:121]
	v_lshl_add_u64 v[114:115], v[116:117], 2, s[30:31]
	v_mad_i64_i32 v[116:117], s[6:7], v116, s18, v[120:121]
	v_mad_i64_i32 v[120:121], s[6:7], v122, s18, v[120:121]
	s_mul_hi_u32 s6, s10, 0x1745d18
	v_ashrrev_i32_e32 v123, 31, v122
	s_lshl_b32 s10, s6, 8
	s_mul_i32 s6, s6, 0x160000
	v_lshl_add_u64 v[118:119], v[122:123], 2, s[30:31]
	v_lshl_add_u64 v[122:123], v[58:59], 0, s[10:11]
	s_or_b32 s10, s6, s48
	v_lshl_add_u64 v[124:125], v[60:61], 0, s[10:11]
	s_mov_b64 s[48:49], 0
	v_mov_b32_e32 v165, v164
	s_andn2_b64 vcc, exec, s[12:13]
	s_cbranch_vccnz .LBB0_721
	s_mov_b64 s[58:59], 0xb000
	v_lshl_add_u64 v[234:235], v[124:125], 0, v[2:3]
	v_mov_b32_e32 v236, v122
	v_mov_b32_e32 v237, v123
	global_load_dword v166, v[234:235], off
	v_lshl_add_u64 v[234:235], v[234:235], 0, s[58:59]
	global_load_dword v167, v[234:235], off
	v_lshl_add_u64 v[234:235], v[234:235], 0, s[58:59]
	global_load_dword v168, v[234:235], off
	v_lshl_add_u64 v[234:235], v[234:235], 0, s[58:59]
	global_load_dword v169, v[234:235], off
	v_lshl_add_u64 v[234:235], v[234:235], 0, s[58:59]
	global_load_dword v170, v[234:235], off
	v_lshl_add_u64 v[234:235], v[234:235], 0, s[58:59]
	global_load_dword v171, v[234:235], off
	v_lshl_add_u64 v[234:235], v[234:235], 0, s[58:59]
	global_load_dword v172, v[234:235], off
	v_lshl_add_u64 v[234:235], v[234:235], 0, s[58:59]
	global_load_dword v173, v[234:235], off
	v_lshl_add_u64 v[234:235], v[234:235], 0, s[58:59]
	global_load_dword v174, v[234:235], off
	v_lshl_add_u64 v[234:235], v[234:235], 0, s[58:59]
	global_load_dword v175, v[234:235], off
	v_lshl_add_u64 v[234:235], v[234:235], 0, s[58:59]
	global_load_dword v176, v[234:235], off
	v_lshl_add_u64 v[234:235], v[234:235], 0, s[58:59]
	global_load_dword v177, v[234:235], off
	v_lshl_add_u64 v[234:235], v[234:235], 0, s[58:59]
	global_load_dword v178, v[234:235], off
	v_lshl_add_u64 v[234:235], v[234:235], 0, s[58:59]
	global_load_dword v179, v[234:235], off
	v_lshl_add_u64 v[234:235], v[234:235], 0, s[58:59]
	global_load_dword v180, v[234:235], off
	v_lshl_add_u64 v[234:235], v[234:235], 0, s[58:59]
	global_load_dword v181, v[234:235], off
	v_lshl_add_u64 v[234:235], v[234:235], 0, s[58:59]
	global_load_dword v182, v[234:235], off
	v_lshl_add_u64 v[234:235], v[234:235], 0, s[58:59]
	global_load_dword v183, v[234:235], off
	v_lshl_add_u64 v[234:235], v[234:235], 0, s[58:59]
	global_load_dword v184, v[234:235], off
	v_lshl_add_u64 v[234:235], v[234:235], 0, s[58:59]
	global_load_dword v185, v[234:235], off
	v_lshl_add_u64 v[234:235], v[234:235], 0, s[58:59]
	global_load_dword v186, v[234:235], off
	v_lshl_add_u64 v[234:235], v[234:235], 0, s[58:59]
	global_load_dword v187, v[234:235], off
	v_lshl_add_u64 v[234:235], v[234:235], 0, s[58:59]
; template <bool GU>
; __device__ __forceinline__ void transpose_item(const float* W, int K, int N, bf16* WT, const float* gs, LAS float* scr, int item, int lane) {
;     ...
;     for (int i = 0; i < 32; ++i) { const int kk = 2 * i + (lane >> 5); float w = W[(size_t)(k0 + kk) * N + n0 + (lane & 31)]; if (gs) w *= gs[k0 + kk]; scr[kk * 33 + (lane & 31)] = w; }
	global_load_dword v188, v[234:235], off
	v_lshl_add_u64 v[234:235], v[234:235], 0, s[58:59]
	global_load_dword v189, v[234:235], off
	v_lshl_add_u64 v[234:235], v[234:235], 0, s[58:59]
	global_load_dword v190, v[234:235], off
	v_lshl_add_u64 v[234:235], v[234:235], 0, s[58:59]
	global_load_dword v191, v[234:235], off
	v_lshl_add_u64 v[234:235], v[234:235], 0, s[58:59]
	global_load_dword v192, v[234:235], off
	v_lshl_add_u64 v[234:235], v[234:235], 0, s[58:59]
	global_load_dword v193, v[234:235], off
	v_lshl_add_u64 v[234:235], v[234:235], 0, s[58:59]
	global_load_dword v194, v[234:235], off
	v_lshl_add_u64 v[234:235], v[234:235], 0, s[58:59]
	global_load_dword v195, v[234:235], off
	v_lshl_add_u64 v[234:235], v[234:235], 0, s[58:59]
	global_load_dword v199, v[234:235], off
	v_lshl_add_u64 v[234:235], v[234:235], 0, s[58:59]
	global_load_dword v200, v[234:235], off
	global_load_dword v201, v[236:237], off
	global_load_dword v202, v[236:237], off offset:8
	global_load_dword v203, v[236:237], off offset:16
	global_load_dword v204, v[236:237], off offset:24
	global_load_dword v205, v[236:237], off offset:32
	global_load_dword v206, v[236:237], off offset:40
	global_load_dword v207, v[236:237], off offset:48
	global_load_dword v208, v[236:237], off offset:56
	global_load_dword v209, v[236:237], off offset:64
	global_load_dword v210, v[236:237], off offset:72
	global_load_dword v211, v[236:237], off offset:80
	global_load_dword v212, v[236:237], off offset:88
	global_load_dword v213, v[236:237], off offset:96
	global_load_dword v214, v[236:237], off offset:104
	global_load_dword v215, v[236:237], off offset:112
	global_load_dword v216, v[236:237], off offset:120
	global_load_dword v217, v[236:237], off offset:128
	global_load_dword v218, v[236:237], off offset:136
	global_load_dword v219, v[236:237], off offset:144
	global_load_dword v220, v[236:237], off offset:152
	global_load_dword v221, v[236:237], off offset:160
	global_load_dword v222, v[236:237], off offset:168
	global_load_dword v223, v[236:237], off offset:176
	global_load_dword v224, v[236:237], off offset:184
	global_load_dword v225, v[236:237], off offset:192
	global_load_dword v226, v[236:237], off offset:200
	global_load_dword v227, v[236:237], off offset:208
	global_load_dword v228, v[236:237], off offset:216
	global_load_dword v229, v[236:237], off offset:224
	global_load_dword v230, v[236:237], off offset:232
	global_load_dword v231, v[236:237], off offset:240
	global_load_dword v232, v[236:237], off offset:248
	s_waitcnt vmcnt(31)
	v_mul_f32_e32 v166, v166, v201
	ds_write_b32 v165, v166
	s_waitcnt vmcnt(30)
	v_mul_f32_e32 v167, v167, v202
	ds_write_b32 v165, v167 offset:264
	s_waitcnt vmcnt(29)
	v_mul_f32_e32 v168, v168, v203
	ds_write_b32 v165, v168 offset:528
	s_waitcnt vmcnt(28)
	v_mul_f32_e32 v169, v169, v204
	ds_write_b32 v165, v169 offset:792
	s_waitcnt vmcnt(27)
	v_mul_f32_e32 v170, v170, v205
	ds_write_b32 v165, v170 offset:1056
	s_waitcnt vmcnt(26)
	v_mul_f32_e32 v171, v171, v206
	ds_write_b32 v165, v171 offset:1320
	s_waitcnt vmcnt(25)
	v_mul_f32_e32 v172, v172, v207
	ds_write_b32 v165, v172 offset:1584
	s_waitcnt vmcnt(24)
	v_mul_f32_e32 v173, v173, v208
	ds_write_b32 v165, v173 offset:1848
	s_waitcnt vmcnt(23)
	v_mul_f32_e32 v174, v174, v209
	ds_write_b32 v165, v174 offset:2112
	s_waitcnt vmcnt(22)
	v_mul_f32_e32 v175, v175, v210
	ds_write_b32 v165, v175 offset:2376
	s_waitcnt vmcnt(21)
	v_mul_f32_e32 v176, v176, v211
	ds_write_b32 v165, v176 offset:2640
	s_waitcnt vmcnt(20)
	v_mul_f32_e32 v177, v177, v212
	ds_write_b32 v165, v177 offset:2904
	s_waitcnt vmcnt(19)
	v_mul_f32_e32 v178, v178, v213
	ds_write_b32 v165, v178 offset:3168
	s_waitcnt vmcnt(18)
	v_mul_f32_e32 v179, v179, v214
	ds_write_b32 v165, v179 offset:3432
	s_waitcnt vmcnt(17)
	v_mul_f32_e32 v180, v180, v215
	ds_write_b32 v165, v180 offset:3696
	s_waitcnt vmcnt(16)
	v_mul_f32_e32 v181, v181, v216
	ds_write_b32 v165, v181 offset:3960
	s_waitcnt vmcnt(15)
	v_mul_f32_e32 v182, v182, v217
	ds_write_b32 v165, v182 offset:4224
	s_waitcnt vmcnt(14)
	v_mul_f32_e32 v183, v183, v218
	ds_write_b32 v165, v183 offset:4488
	s_waitcnt vmcnt(13)
	v_mul_f32_e32 v184, v184, v219
	ds_write_b32 v165, v184 offset:4752
	s_waitcnt vmcnt(12)
	v_mul_f32_e32 v185, v185, v220
	ds_write_b32 v165, v185 offset:5016
	s_waitcnt vmcnt(11)
	v_mul_f32_e32 v186, v186, v221
	ds_write_b32 v165, v186 offset:5280
	s_waitcnt vmcnt(10)
	v_mul_f32_e32 v187, v187, v222
	ds_write_b32 v165, v187 offset:5544
	s_waitcnt vmcnt(9)
	v_mul_f32_e32 v188, v188, v223
	ds_write_b32 v165, v188 offset:5808
	s_waitcnt vmcnt(8)
	v_mul_f32_e32 v189, v189, v224
	ds_write_b32 v165, v189 offset:6072
	s_waitcnt vmcnt(7)
	v_mul_f32_e32 v190, v190, v225
	ds_write_b32 v165, v190 offset:6336
	s_waitcnt vmcnt(6)
	v_mul_f32_e32 v191, v191, v226
	ds_write_b32 v165, v191 offset:6600
	s_waitcnt vmcnt(5)
	v_mul_f32_e32 v192, v192, v227
	ds_write_b32 v165, v192 offset:6864
	s_waitcnt vmcnt(4)
	v_mul_f32_e32 v193, v193, v228
	ds_write_b32 v165, v193 offset:7128
	s_waitcnt vmcnt(3)
	v_mul_f32_e32 v194, v194, v229
	ds_write_b32 v165, v194 offset:7392
	s_waitcnt vmcnt(2)
	v_mul_f32_e32 v195, v195, v230
	ds_write_b32 v165, v195 offset:7656
	s_waitcnt vmcnt(1)
	v_mul_f32_e32 v199, v199, v231
	ds_write_b32 v165, v199 offset:7920
	s_waitcnt vmcnt(0)
	v_mul_f32_e32 v200, v200, v232
	ds_write_b32 v165, v200 offset:8184
	s_branch .LBB0_753

; template <bool GU>
; __device__ __forceinline__ void transpose_item(const float* W, int K, int N, bf16* WT, const float* gs, LAS float* scr, int item, int lane) {
;     const int nblk = N / 32, kb = item / nblk, nb = item % nblk, k0 = 64 * kb, n0 = 32 * nb;
; #pragma unroll 16
;     for (int i = 0; i < 32; ++i) { const int kk = 2 * i + (lane >> 5); float w = W[(size_t)(k0 + kk) * N + n0 + (lane & 31)]; if (gs) w *= gs[k0 + kk]; scr[kk * 33 + (lane & 31)] = w; }
; __device__ __forceinline__ void conv_weights(LAS unsigned char* lds, unsigned char* ws, const PIn& I, const int l, const int wave, const int lane, const int gw, const int NGW, const int r_lo, const int r_hi) {
;     ...
;         if (r < I_IN) { transpose_item<false>(I.w_in + (size_t)l * DM * NIN, DM, NIN, (bf16*)(wb + W_IN), I.g_mix + l * DM, scr, r, lane); continue; } r -= I_IN;
.LBB0_758:
	s_mul_hi_i32 s6, s0, 0x38e38e39
	s_lshr_b32 s7, s6, 31
	s_ashr_i32 s6, s6, 4
	s_add_i32 s6, s6, s7
	s_mul_i32 s7, s6, 0x48
	s_sub_i32 s7, s0, s7
	s_lshl_b32 s48, s7, 5
	s_lshl_b32 s50, s6, 6
	s_ashr_i32 s49, s48, 31
	s_lshl_b64 s[6:7], s[48:49], 2
	s_ashr_i32 s51, s50, 31
	v_lshl_add_u64 v[66:67], v[56:57], 0, s[50:51]
	v_mov_b64_e32 v[68:69], s[6:7]
	v_lshl_add_u64 v[62:63], v[24:25], 0, s[6:7]
	v_mad_u64_u32 v[68:69], s[6:7], v66, s29, v[68:69]
	v_mad_i32_i24 v69, v67, s29, v69
	v_add_u32_e32 v70, s50, v56
	v_lshl_add_u64 v[64:65], v[66:67], 2, s[14:15]
	v_lshl_add_u64 v[66:67], v[24:25], 0, v[68:69]
	s_mov_b32 s10, 0
	v_mov_b32_e32 v71, v164
	s_andn2_b64 vcc, exec, s[16:17]
	s_cbranch_vccnz .LBB0_760
	s_mov_b64 s[58:59], 0x4800
	v_mov_b32_e32 v234, v66
	v_mov_b32_e32 v235, v67
	v_mov_b32_e32 v236, v64
	v_mov_b32_e32 v237, v65
	global_load_dword v166, v[234:235], off
	v_lshl_add_u64 v[234:235], v[234:235], 0, s[58:59]
	global_load_dword v167, v[234:235], off
	v_lshl_add_u64 v[234:235], v[234:235], 0, s[58:59]
	global_load_dword v168, v[234:235], off
	v_lshl_add_u64 v[234:235], v[234:235], 0, s[58:59]
	global_load_dword v169, v[234:235], off
	v_lshl_add_u64 v[234:235], v[234:235], 0, s[58:59]
	global_load_dword v170, v[234:235], off
	v_lshl_add_u64 v[234:235], v[234:235], 0, s[58:59]
	global_load_dword v171, v[234:235], off
	v_lshl_add_u64 v[234:235], v[234:235], 0, s[58:59]
	global_load_dword v172, v[234:235], off
	v_lshl_add_u64 v[234:235], v[234:235], 0, s[58:59]
	global_load_dword v173, v[234:235], off
	v_lshl_add_u64 v[234:235], v[234:235], 0, s[58:59]
	global_load_dword v174, v[234:235], off
	v_lshl_add_u64 v[234:235], v[234:235], 0, s[58:59]
	global_load_dword v175, v[234:235], off
	v_lshl_add_u64 v[234:235], v[234:235], 0, s[58:59]
	global_load_dword v176, v[234:235], off
	v_lshl_add_u64 v[234:235], v[234:235], 0, s[58:59]
	global_load_dword v177, v[234:235], off
	v_lshl_add_u64 v[234:235], v[234:235], 0, s[58:59]
	global_load_dword v178, v[234:235], off
	v_lshl_add_u64 v[234:235], v[234:235], 0, s[58:59]
	global_load_dword v179, v[234:235], off
	v_lshl_add_u64 v[234:235], v[234:235], 0, s[58:59]
	global_load_dword v180, v[234:235], off
	v_lshl_add_u64 v[234:235], v[234:235], 0, s[58:59]
	global_load_dword v181, v[234:235], off
	v_lshl_add_u64 v[234:235], v[234:235], 0, s[58:59]
	global_load_dword v182, v[234:235], off
	v_lshl_add_u64 v[234:235], v[234:235], 0, s[58:59]
	global_load_dword v183, v[234:235], off
	v_lshl_add_u64 v[234:235], v[234:235], 0, s[58:59]
	global_load_dword v184, v[234:235], off
	v_lshl_add_u64 v[234:235], v[234:235], 0, s[58:59]
	global_load_dword v185, v[234:235], off
	v_lshl_add_u64 v[234:235], v[234:235], 0, s[58:59]
	global_load_dword v186, v[234:235], off
	v_lshl_add_u64 v[234:235], v[234:235], 0, s[58:59]
	global_load_dword v187, v[234:235], off
	v_lshl_add_u64 v[234:235], v[234:235], 0, s[58:59]
	global_load_dword v188, v[234:235], off
	v_lshl_add_u64 v[234:235], v[234:235], 0, s[58:59]
	global_load_dword v189, v[234:235], off
	v_lshl_add_u64 v[234:235], v[234:235], 0, s[58:59]
	global_load_dword v190, v[234:235], off
	v_lshl_add_u64 v[234:235], v[234:235], 0, s[58:59]
	global_load_dword v191, v[234:235], off
	v_lshl_add_u64 v[234:235], v[234:235], 0, s[58:59]
	global_load_dword v192, v[234:235], off
	v_lshl_add_u64 v[234:235], v[234:235], 0, s[58:59]
	global_load_dword v193, v[234:235], off
	v_lshl_add_u64 v[234:235], v[234:235], 0, s[58:59]
	global_load_dword v194, v[234:235], off
	v_lshl_add_u64 v[234:235], v[234:235], 0, s[58:59]
	global_load_dword v195, v[234:235], off
	v_lshl_add_u64 v[234:235], v[234:235], 0, s[58:59]
	global_load_dword v199, v[234:235], off
	v_lshl_add_u64 v[234:235], v[234:235], 0, s[58:59]
	global_load_dword v200, v[234:235], off
	global_load_dword v201, v[236:237], off
	global_load_dword v202, v[236:237], off offset:8
	global_load_dword v203, v[236:237], off offset:16
	global_load_dword v204, v[236:237], off offset:24
	global_load_dword v205, v[236:237], off offset:32
	global_load_dword v206, v[236:237], off offset:40
	global_load_dword v207, v[236:237], off offset:48
	global_load_dword v208, v[236:237], off offset:56
	global_load_dword v209, v[236:237], off offset:64
	global_load_dword v210, v[236:237], off offset:72
	global_load_dword v211, v[236:237], off offset:80
	global_load_dword v212, v[236:237], off offset:88
	global_load_dword v213, v[236:237], off offset:96
	global_load_dword v214, v[236:237], off offset:104
	global_load_dword v215, v[236:237], off offset:112
	global_load_dword v216, v[236:237], off offset:120
	global_load_dword v217, v[236:237], off offset:128
	global_load_dword v218, v[236:237], off offset:136
	global_load_dword v219, v[236:237], off offset:144
	global_load_dword v220, v[236:237], off offset:152
	global_load_dword v221, v[236:237], off offset:160
	global_load_dword v222, v[236:237], off offset:168
	global_load_dword v223, v[236:237], off offset:176
	global_load_dword v224, v[236:237], off offset:184
	global_load_dword v225, v[236:237], off offset:192
	global_load_dword v226, v[236:237], off offset:200
	global_load_dword v227, v[236:237], off offset:208
	global_load_dword v228, v[236:237], off offset:216
	global_load_dword v229, v[236:237], off offset:224
	global_load_dword v230, v[236:237], off offset:232
	global_load_dword v231, v[236:237], off offset:240
	global_load_dword v232, v[236:237], off offset:248
	s_waitcnt vmcnt(31)
; template <bool GU>
; __device__ __forceinline__ void transpose_item(const float* W, int K, int N, bf16* WT, const float* gs, LAS float* scr, int item, int lane) {
;     ...
;     for (int i = 0; i < 32; ++i) { const int kk = 2 * i + (lane >> 5); float w = W[(size_t)(k0 + kk) * N + n0 + (lane & 31)]; if (gs) w *= gs[k0 + kk]; scr[kk * 33 + (lane & 31)] = w; }
	v_mul_f32_e32 v166, v166, v201
	ds_write_b32 v71, v166
	s_waitcnt vmcnt(30)
	v_mul_f32_e32 v167, v167, v202
	ds_write_b32 v71, v167 offset:264
	s_waitcnt vmcnt(29)
	v_mul_f32_e32 v168, v168, v203
	ds_write_b32 v71, v168 offset:528
	s_waitcnt vmcnt(28)
	v_mul_f32_e32 v169, v169, v204
	ds_write_b32 v71, v169 offset:792
	s_waitcnt vmcnt(27)
	v_mul_f32_e32 v170, v170, v205
	ds_write_b32 v71, v170 offset:1056
	s_waitcnt vmcnt(26)
	v_mul_f32_e32 v171, v171, v206
	ds_write_b32 v71, v171 offset:1320
	s_waitcnt vmcnt(25)
	v_mul_f32_e32 v172, v172, v207
	ds_write_b32 v71, v172 offset:1584
	s_waitcnt vmcnt(24)
	v_mul_f32_e32 v173, v173, v208
	ds_write_b32 v71, v173 offset:1848
	s_waitcnt vmcnt(23)
	v_mul_f32_e32 v174, v174, v209
	ds_write_b32 v71, v174 offset:2112
	s_waitcnt vmcnt(22)
	v_mul_f32_e32 v175, v175, v210
	ds_write_b32 v71, v175 offset:2376
	s_waitcnt vmcnt(21)
	v_mul_f32_e32 v176, v176, v211
	ds_write_b32 v71, v176 offset:2640
	s_waitcnt vmcnt(20)
	v_mul_f32_e32 v177, v177, v212
	ds_write_b32 v71, v177 offset:2904
	s_waitcnt vmcnt(19)
	v_mul_f32_e32 v178, v178, v213
	ds_write_b32 v71, v178 offset:3168
	s_waitcnt vmcnt(18)
	v_mul_f32_e32 v179, v179, v214
	ds_write_b32 v71, v179 offset:3432
	s_waitcnt vmcnt(17)
	v_mul_f32_e32 v180, v180, v215
	ds_write_b32 v71, v180 offset:3696
	s_waitcnt vmcnt(16)
	v_mul_f32_e32 v181, v181, v216
	ds_write_b32 v71, v181 offset:3960
	s_waitcnt vmcnt(15)
	v_mul_f32_e32 v182, v182, v217
	ds_write_b32 v71, v182 offset:4224
	s_waitcnt vmcnt(14)
	v_mul_f32_e32 v183, v183, v218
	ds_write_b32 v71, v183 offset:4488
	s_waitcnt vmcnt(13)
	v_mul_f32_e32 v184, v184, v219
	ds_write_b32 v71, v184 offset:4752
	s_waitcnt vmcnt(12)
	v_mul_f32_e32 v185, v185, v220
	ds_write_b32 v71, v185 offset:5016
	s_waitcnt vmcnt(11)
	v_mul_f32_e32 v186, v186, v221
	ds_write_b32 v71, v186 offset:5280
	s_waitcnt vmcnt(10)
	v_mul_f32_e32 v187, v187, v222
	ds_write_b32 v71, v187 offset:5544
	s_waitcnt vmcnt(9)
	v_mul_f32_e32 v188, v188, v223
	ds_write_b32 v71, v188 offset:5808
	s_waitcnt vmcnt(8)
	v_mul_f32_e32 v189, v189, v224
	ds_write_b32 v71, v189 offset:6072
	s_waitcnt vmcnt(7)
	v_mul_f32_e32 v190, v190, v225
	ds_write_b32 v71, v190 offset:6336
	s_waitcnt vmcnt(6)
	v_mul_f32_e32 v191, v191, v226
	ds_write_b32 v71, v191 offset:6600
	s_waitcnt vmcnt(5)
	v_mul_f32_e32 v192, v192, v227
	ds_write_b32 v71, v192 offset:6864
	s_waitcnt vmcnt(4)
	v_mul_f32_e32 v193, v193, v228
	ds_write_b32 v71, v193 offset:7128
	s_waitcnt vmcnt(3)
	v_mul_f32_e32 v194, v194, v229
	ds_write_b32 v71, v194 offset:7392
	s_waitcnt vmcnt(2)
	v_mul_f32_e32 v195, v195, v230
	ds_write_b32 v71, v195 offset:7656
	s_waitcnt vmcnt(1)
	v_mul_f32_e32 v199, v199, v231
	ds_write_b32 v71, v199 offset:7920
	s_waitcnt vmcnt(0)
	v_mul_f32_e32 v200, v200, v232
	ds_write_b32 v71, v200 offset:8184
	s_branch .LBB0_703
